# attention fast loops: static s_setprio 1 for the OTHER wave half (waves 0-3) - mirror of the previous version
# speedup vs baseline: 1.0079x; 1.0040x over previous
; __device__ __forceinline__ int swz(int row) { return ((row & 3) << 2) | ((row >> 2) & 3); }
; __device__ __forceinline__ void dma_tile(const bf16* kbase, const bf16* vbase, int key0, ldsp stage, int wave, int lane) {
;     ...
;     for (int j = 0; j < 2; ++j) { const int rowb = 8 * wave + 4 * j, row = rowb + (lane >> 4), cc = (lane & 15) ^ swz(row); const size_t off = (size_t)(key0 + row) * 128 + cc * 8;
;         glds16(kbase + off, sb + rowb * 256);
;         glds16(vbase + off, sb + RKV + rowb * 256); }
; __device__ __forceinline__ void diff_unit(const bf16* proj, bf16* og0, const float* nwv, float lam_full, float one_m_li, int h, int qb, ldsp lds, int tid, int lane, int wave, int mode) {
;     ...
;     for (int i = 2; i < nt; ++i) {
;         asm volatile("s_waitcnt vmcnt(8)" ::: "memory");
;         __builtin_amdgcn_s_barrier();
;         asm volatile("" ::: "memory");
;         { int n = i + 3; n = n < nt ? n : nt - 1; dma_tile(kbase, vbase, 64 * (n - 2), lds + ((i + 3) & 3) * RSTG, wave, lane); }
;         ldsp Ks = lds + (i & 3) * RSTG, Vs = Ks + RKV;
;         flash_fast_tile2<4>(Ks, Vs, M, qf, o, mc, l);
.LBB0_433:
	s_mov_b32 s6, 2
	s_add_i32 s7, s9, 2
	s_or_b32 s8, s9, 1
	s_cmp_lt_u32 5, s7
	s_cselect_b32 s1, 5, s8
	v_lshl_add_u32 v223, s1, 6, v183
	v_add_u32_e32 v225, s35, v223
	v_add_u32_e32 v223, s31, v223
	v_lshlrev_b32_e32 v225, 8, v225
	v_lshlrev_b32_e32 v223, 8, v223
	v_lshl_add_u32 v225, v156, 1, v225
	v_lshl_add_u32 v223, v154, 1, v223
	s_and_b64 vcc, exec, s[20:21]
	s_cbranch_vccnz .Lap_skip1
	s_setprio 1

; __device__ __forceinline__ int swz(int row) { return ((row & 3) << 2) | ((row >> 2) & 3); }
; __device__ __forceinline__ void dma_tile(const bf16* kbase, const bf16* vbase, int key0, ldsp stage, int wave, int lane) {
;     ...
;     for (int j = 0; j < 2; ++j) { const int rowb = 8 * wave + 4 * j, row = rowb + (lane >> 4), cc = (lane & 15) ^ swz(row); const size_t off = (size_t)(key0 + row) * 128 + cc * 8;
;         glds16(kbase + off, sb + rowb * 256);
;         glds16(vbase + off, sb + RKV + rowb * 256); }
; __device__ __forceinline__ void diff_unit(const bf16* proj, bf16* og0, const float* nwv, float lam_full, float one_m_li, int h, int qb, ldsp lds, int tid, int lane, int wave, int mode) {
;     ...
;     for (int i = 2; i < nt; ++i) {
;         asm volatile("s_waitcnt vmcnt(8)" ::: "memory");
;         __builtin_amdgcn_s_barrier();
;         asm volatile("" ::: "memory");
;         { int n = i + 3; n = n < nt ? n : nt - 1; dma_tile(kbase, vbase, 64 * (n - 2), lds + ((i + 3) & 3) * RSTG, wave, lane); }
;         ldsp Ks = lds + (i & 3) * RSTG, Vs = Ks + RKV;
;         flash_fast_tile2<4>(Ks, Vs, M, qf, o, mc, l);
.LBB0_456:
	s_andn2_b64 vcc, exec, s[28:29]
	s_cbranch_vccnz .LBB0_465
	s_mov_b32 s6, 2
	s_cmp_lt_i32 5, s59
	s_cselect_b32 s1, 5, s60
	v_lshl_add_u32 v223, s1, 6, v183
	v_add_u32_e32 v225, s35, v223
	v_add_u32_e32 v223, s31, v223
	v_lshlrev_b32_e32 v225, 8, v225
	v_lshlrev_b32_e32 v223, 8, v223
	v_lshl_add_u32 v225, v156, 1, v225
	v_lshl_add_u32 v223, v154, 1, v223
	s_and_b64 vcc, exec, s[20:21]
	s_cbranch_vccnz .Lap_skip2
	s_setprio 1
